# L0 out-proj epilogue pass 1: f32 residual loads into a 7-quad spare-VGPR pool, first 7 issued before the row statistics, rest rotated ahead
# baseline (speedup 1.0000x reference)
.LBB0_570:
	s_lshl_b32 s100, s17, 5
	s_lshl_b32 s101, s18, 8
	s_or_b32 s100, s101, s100
	v_lshrrev_b32_e32 v250, 2, v148
	v_and_or_b32 v250, v250, 12, s100
	s_lshl_b32 s100, s16, 8
	v_add_u32_e32 v231, s100, v152
	v_lshlrev_b32_e32 v231, 12, v231
	v_lshl_add_u32 v231, v250, 2, v231
	v_readlane_b32 s100, v251, 25
	v_readlane_b32 s101, v251, 26
	s_nop 4
	global_load_dwordx4 v[216:219], v231, s[100:101]
	global_load_dwordx4 v[220:223], v231, s[100:101] offset:64
	global_load_dwordx4 v[232:235], v231, s[100:101] offset:512
	global_load_dwordx4 v[236:239], v231, s[100:101] offset:576
	v_add_u32_e32 v250, 0x10000, v231
	global_load_dwordx4 v[240:243], v250, s[100:101]
	global_load_dwordx4 v[244:247], v250, s[100:101] offset:64
	global_load_dwordx4 v[252:255], v250, s[100:101] offset:512
	v_mov_b32_e32 v130, v127
	v_mov_b32_e32 v131, v128
	v_mov_b32_e32 v132, v126
	v_mov_b32_e32 v133, v129
	v_pk_add_f32 v[130:131], v[130:131], v[132:133]
	v_mov_b32_e32 v132, v123
	v_mov_b32_e32 v133, v124
	v_mov_b32_e32 v134, v122
	v_mov_b32_e32 v135, v125
	v_pk_add_f32 v[132:133], v[132:133], v[134:135]
	v_add_f32_e32 v130, v130, v131
	v_pk_add_f32 v[132:133], v[132:133], v[132:133] op_sel_hi:[0,1]
	v_add_f32_e32 v131, 0, v130
	v_add_f32_e32 v135, v118, v119
	v_add_f32_e32 v137, v120, v121
	v_mov_b32_e32 v134, v114
	v_mov_b32_e32 v136, v115
	v_mov_b32_e32 v132, v116
	v_mov_b32_e32 v130, v117
	v_pk_add_f32 v[134:135], v[134:135], v[136:137]
	v_pk_add_f32 v[130:131], v[132:133], v[130:131]
	v_mov_b32_e32 v133, v126
	v_pk_add_f32 v[130:131], v[134:135], v[130:131]
	v_mov_b32_e32 v134, v127
	v_add_f32_e32 v130, v130, v131
	v_mov_b32_e32 v131, v130
	s_nop 1
	v_permlane16_swap_b32_e32 v130, v131
	v_mov_b32_e32 v135, v123
	s_lshl_b32 s0, s17, 3
	s_add_i32 s27, s0, 0
	s_barrier
	s_waitcnt lgkmcnt(0)
	v_add_f32_e32 v130, v130, v131
	v_mov_b32_e32 v131, v130
	s_nop 1
	v_permlane32_swap_b32_e32 v130, v131
	s_waitcnt lgkmcnt(0)
	v_add_f32_e32 v131, v130, v131
	v_fmamk_f32 v132, v131, 0xbc800000, v129
	v_fmac_f32_e32 v134, 0xbc800000, v131
	v_fmamk_f32 v130, v131, 0xbc800000, v128
	v_fmac_f32_e32 v133, 0xbc800000, v131
	v_mul_f32_e32 v134, v134, v134
	v_mul_f32_e32 v132, v132, v132
	v_fmac_f32_e32 v134, v133, v133
	v_fmac_f32_e32 v132, v130, v130
	v_add_f32_e32 v130, v134, v132
	v_fmamk_f32 v133, v131, 0xbc800000, v125
	v_mov_b32_e32 v134, v122
	v_fmac_f32_e32 v135, 0xbc800000, v131
	v_fmamk_f32 v132, v131, 0xbc800000, v124
	v_fmac_f32_e32 v134, 0xbc800000, v131
	v_mul_f32_e32 v135, v135, v135
	v_mul_f32_e32 v133, v133, v133
	v_fmac_f32_e32 v135, v134, v134
	v_fmac_f32_e32 v133, v132, v132
	v_add_f32_e32 v132, v135, v133
	v_mov_b32_e32 v135, v119
	v_fmamk_f32 v133, v131, 0xbc800000, v121
	v_mov_b32_e32 v134, v118
	v_fmac_f32_e32 v135, 0xbc800000, v131
	v_add_f32_e32 v130, v130, v132
	v_fmamk_f32 v132, v131, 0xbc800000, v120
	v_fmac_f32_e32 v134, 0xbc800000, v131
	v_mul_f32_e32 v135, v135, v135
	v_mul_f32_e32 v133, v133, v133
	v_fmac_f32_e32 v135, v134, v134
	v_fmac_f32_e32 v133, v132, v132
	v_add_f32_e32 v132, v135, v133
	v_mov_b32_e32 v135, v115
	v_fmamk_f32 v133, v131, 0xbc800000, v117
	v_mov_b32_e32 v134, v114
	v_fmac_f32_e32 v135, 0xbc800000, v131
	v_add_f32_e32 v130, v132, v130
	v_fmamk_f32 v132, v131, 0xbc800000, v116
	v_fmac_f32_e32 v134, 0xbc800000, v131
	v_mul_f32_e32 v135, v135, v135
	v_mul_f32_e32 v133, v133, v133
	v_fmac_f32_e32 v135, v134, v134
	v_fmac_f32_e32 v133, v132, v132
	v_add_f32_e32 v132, v135, v133
	v_add_f32_e32 v132, v132, v130
	v_mov_b32_e32 v133, v132
	s_nop 1
	v_permlane16_swap_b32_e32 v132, v133
	v_and_b32_e32 v130, 63, v148
	v_cmp_gt_u32_e64 s[4:5], 16, v130
	s_waitcnt lgkmcnt(0)
	v_add_f32_e32 v132, v132, v133
	v_mov_b32_e32 v133, v132
	s_nop 1
	v_permlane32_swap_b32_e32 v132, v133
	s_and_saveexec_b64 s[0:1], s[4:5]
	s_cbranch_execz .LBB0_572
	s_lshl_b32 s6, s26, 11
	s_add_i32 s6, s27, s6
	v_mul_f32_e32 v134, 0x3c800000, v131
	s_waitcnt lgkmcnt(0)
	v_add_f32_e32 v135, v132, v133
	v_lshl_add_u32 v131, v170, 5, s6
	ds_write_b64 v131, v[134:135]

.LBB0_610:
	s_or_b64 exec, exec, s[22:23]
	s_lshl_b32 s0, s17, 5
	s_lshl_b32 s1, s18, 8
	s_or_b32 s0, s1, s0
	v_lshrrev_b32_e32 v130, 2, v148
	v_and_or_b32 v162, v130, 12, s0
	s_lshl_b32 s0, s16, 5
	s_and_b32 s0, s0, 0xfffffc00
	v_add_u32_e32 v148, s0, v162
	v_readlane_b32 s0, v251, 45
	v_add_u32_e32 v150, s19, v152
	v_readlane_b32 s40, v251, 25
	v_ashrrev_i32_e32 v149, 31, v148
	v_readlane_b32 s1, v251, 46
	v_ashrrev_i32_e32 v151, 31, v150
	v_readlane_b32 s41, v251, 26
	v_lshl_add_u64 v[138:139], v[148:149], 2, s[0:1]
	v_ashrrev_i32_e32 v163, 31, v162
	v_lshlrev_b64 v[130:131], 12, v[150:151]
	s_mov_b64 s[0:1], s[40:41]
	v_lshl_add_u64 v[130:131], s[0:1], 0, v[130:131]
	v_lshlrev_b64 v[168:169], 2, v[162:163]
	s_waitcnt lgkmcnt(0)
	s_barrier
	v_lshl_add_u64 v[172:173], v[130:131], 0, v[168:169]
	global_load_dwordx4 v[134:137], v[138:139], off
	s_waitcnt lgkmcnt(0)
	global_load_dwordx4 v[130:133], v[138:139], off offset:64
	global_load_dwordx4 v[142:145], v[138:139], off offset:512
	s_nop 0
	global_load_dwordx4 v[138:141], v[138:139], off offset:576
	s_nop 0
	v_lshl_add_u32 v184, v152, 3, 0
	ds_read_b64 v[176:177], v184 offset:8192
	v_add_u32_e32 v152, 16, v150
	v_ashrrev_i32_e32 v153, 31, v152
	v_lshlrev_b64 v[178:179], 12, v[152:153]
	v_lshl_add_u64 v[178:179], s[0:1], 0, v[178:179]
	s_waitcnt lgkmcnt(0)
	v_pk_mul_f32 v[126:127], v[126:127], v[176:177] op_sel:[0,1]
	v_pk_mul_f32 v[128:129], v[128:129], v[176:177] op_sel:[0,1]
	v_pk_mul_f32 v[122:123], v[122:123], v[176:177] op_sel:[0,1]
	v_pk_mul_f32 v[124:125], v[124:125], v[176:177] op_sel:[0,1]
	v_pk_mul_f32 v[180:181], v[118:119], v[176:177] op_sel:[0,1]
	v_pk_mul_f32 v[188:189], v[120:121], v[176:177] op_sel:[0,1]
	v_pk_mul_f32 v[114:115], v[114:115], v[176:177] op_sel:[0,1]
	v_pk_mul_f32 v[116:117], v[116:117], v[176:177] op_sel:[0,1]
	v_lshl_add_u64 v[178:179], v[178:179], 0, v[168:169]
	v_readlane_b32 s42, v251, 27
	v_readlane_b32 s43, v251, 28
	v_readlane_b32 s44, v251, 29
	v_readlane_b32 s45, v251, 30
	v_readlane_b32 s46, v251, 31
	v_readlane_b32 s47, v251, 32
	v_readlane_b32 s48, v251, 33
	v_readlane_b32 s49, v251, 34
	v_readlane_b32 s50, v251, 35
	v_readlane_b32 s51, v251, 36
	v_readlane_b32 s52, v251, 37
	v_readlane_b32 s53, v251, 38
	v_readlane_b32 s54, v251, 39
	v_readlane_b32 s55, v251, 40
	s_waitcnt vmcnt(3)
	v_pk_fma_f32 v[120:121], v[136:137], v[128:129], v[218:219]
	v_pk_fma_f32 v[118:119], v[134:135], v[126:127], v[216:217]
	s_waitcnt vmcnt(2)
	v_pk_fma_f32 v[124:125], v[132:133], v[124:125], v[222:223]
	v_pk_fma_f32 v[122:123], v[130:131], v[122:123], v[220:221]
	s_waitcnt vmcnt(1)
	v_pk_fma_f32 v[128:129], v[144:145], v[188:189], v[234:235]
	v_pk_fma_f32 v[126:127], v[142:143], v[180:181], v[232:233]
	s_waitcnt vmcnt(0)
	v_pk_fma_f32 v[116:117], v[140:141], v[116:117], v[238:239]
	v_pk_fma_f32 v[114:115], v[138:139], v[114:115], v[236:237]
	v_add_u32_e32 v154, 32, v150
	v_add_u32_e32 v250, 0x10000, v231
	global_load_dwordx4 v[216:219], v250, s[100:101] offset:576
	v_add_u32_e32 v250, 0x20000, v231
	global_load_dwordx4 v[220:223], v250, s[100:101]
	global_load_dwordx4 v[232:235], v250, s[100:101] offset:64
	global_load_dwordx4 v[236:239], v250, s[100:101] offset:512
	s_nop 0
	ds_read_b64 v[160:161], v184 offset:8320
	v_ashrrev_i32_e32 v155, 31, v154
	v_lshlrev_b64 v[180:181], 12, v[154:155]
	v_lshl_add_u64 v[180:181], s[0:1], 0, v[180:181]
	v_lshl_add_u64 v[180:181], v[180:181], 0, v[168:169]
	s_waitcnt lgkmcnt(0)
	v_pk_mul_f32 v[110:111], v[110:111], v[160:161] op_sel:[0,1]
	v_pk_mul_f32 v[112:113], v[112:113], v[160:161] op_sel:[0,1]
	v_pk_mul_f32 v[106:107], v[106:107], v[160:161] op_sel:[0,1]
	v_pk_mul_f32 v[108:109], v[108:109], v[160:161] op_sel:[0,1]
	v_pk_mul_f32 v[102:103], v[102:103], v[160:161] op_sel:[0,1]
	v_pk_mul_f32 v[104:105], v[104:105], v[160:161] op_sel:[0,1]
	v_pk_mul_f32 v[98:99], v[98:99], v[160:161] op_sel:[0,1]
	v_pk_mul_f32 v[100:101], v[100:101], v[160:161] op_sel:[0,1]
	v_mov_b32_e32 v196, v118
	v_mov_b32_e32 v197, v121
	v_mov_b32_e32 v204, v123
	v_mov_b32_e32 v205, v124
	v_mov_b32_e32 v206, v122
	v_mov_b32_e32 v207, v125
	v_add_f32_e32 v209, v126, v127
	v_add_f32_e32 v213, v128, v129
	v_mov_b32_e32 v208, v114
	v_mov_b32_e32 v212, v115
	v_mov_b32_e32 v214, v117
	s_waitcnt vmcnt(10)
	v_pk_fma_f32 v[112:113], v[136:137], v[112:113], v[242:243]
	v_pk_fma_f32 v[110:111], v[134:135], v[110:111], v[240:241]
	s_waitcnt vmcnt(9)
	v_pk_fma_f32 v[108:109], v[132:133], v[108:109], v[246:247]
	v_pk_fma_f32 v[106:107], v[130:131], v[106:107], v[244:245]
	s_waitcnt vmcnt(8)
	v_pk_fma_f32 v[104:105], v[144:145], v[104:105], v[254:255]
	v_pk_fma_f32 v[102:103], v[142:143], v[102:103], v[252:253]
	s_waitcnt vmcnt(3)
	v_pk_fma_f32 v[100:101], v[140:141], v[100:101], v[218:219]
	v_pk_fma_f32 v[98:99], v[138:139], v[98:99], v[216:217]
	v_add_u32_e32 v156, 48, v150
	v_add_u32_e32 v250, 0x20000, v231
	global_load_dwordx4 v[240:243], v250, s[100:101] offset:576
	v_add_u32_e32 v250, 0x30000, v231
	global_load_dwordx4 v[244:247], v250, s[100:101]
	global_load_dwordx4 v[252:255], v250, s[100:101] offset:64
	global_load_dwordx4 v[216:219], v250, s[100:101] offset:512
	ds_read_b64 v[180:181], v184 offset:8448
	v_ashrrev_i32_e32 v157, 31, v156
	v_lshlrev_b64 v[188:189], 12, v[156:157]
	v_lshl_add_u64 v[188:189], s[0:1], 0, v[188:189]
	v_lshl_add_u64 v[188:189], v[188:189], 0, v[168:169]
	s_waitcnt lgkmcnt(0)
	v_pk_mul_f32 v[94:95], v[94:95], v[180:181] op_sel:[0,1]
	v_pk_mul_f32 v[96:97], v[96:97], v[180:181] op_sel:[0,1]
	v_pk_mul_f32 v[90:91], v[90:91], v[180:181] op_sel:[0,1]
	v_pk_mul_f32 v[92:93], v[92:93], v[180:181] op_sel:[0,1]
	v_pk_mul_f32 v[86:87], v[86:87], v[180:181] op_sel:[0,1]
	v_pk_mul_f32 v[88:89], v[88:89], v[180:181] op_sel:[0,1]
	v_pk_mul_f32 v[82:83], v[82:83], v[180:181] op_sel:[0,1]
	v_pk_mul_f32 v[84:85], v[84:85], v[180:181] op_sel:[0,1]
	s_waitcnt vmcnt(6)
	v_pk_fma_f32 v[96:97], v[136:137], v[96:97], v[222:223]
	v_pk_fma_f32 v[94:95], v[134:135], v[94:95], v[220:221]
	s_waitcnt vmcnt(5)
	v_pk_fma_f32 v[92:93], v[132:133], v[92:93], v[234:235]
	v_pk_fma_f32 v[90:91], v[130:131], v[90:91], v[232:233]
	s_waitcnt vmcnt(4)
	v_pk_fma_f32 v[88:89], v[144:145], v[88:89], v[238:239]
	v_pk_fma_f32 v[86:87], v[142:143], v[86:87], v[236:237]
	s_waitcnt vmcnt(3)
	v_pk_fma_f32 v[84:85], v[140:141], v[84:85], v[242:243]
	v_pk_fma_f32 v[82:83], v[138:139], v[82:83], v[240:241]
	v_add_u32_e32 v158, 0x80, v150
	v_add_u32_e32 v250, 0x30000, v231
	global_load_dwordx4 v[220:223], v250, s[100:101] offset:576
	v_add_u32_e32 v250, 0x80000, v231
	global_load_dwordx4 v[232:235], v250, s[100:101]
	global_load_dwordx4 v[236:239], v250, s[100:101] offset:64
	global_load_dwordx4 v[240:243], v250, s[100:101] offset:512
	s_nop 0
	ds_read_b64 v[160:161], v184 offset:8576
	v_ashrrev_i32_e32 v159, 31, v158
	v_lshlrev_b64 v[180:181], 12, v[158:159]
	v_lshl_add_u64 v[180:181], s[0:1], 0, v[180:181]
	v_lshl_add_u64 v[180:181], v[180:181], 0, v[168:169]
	s_waitcnt lgkmcnt(0)
	v_pk_mul_f32 v[78:79], v[78:79], v[160:161] op_sel:[0,1]
	v_pk_mul_f32 v[80:81], v[80:81], v[160:161] op_sel:[0,1]
	v_pk_mul_f32 v[74:75], v[74:75], v[160:161] op_sel:[0,1]
	v_pk_mul_f32 v[76:77], v[76:77], v[160:161] op_sel:[0,1]
	v_pk_mul_f32 v[70:71], v[70:71], v[160:161] op_sel:[0,1]
	v_pk_mul_f32 v[72:73], v[72:73], v[160:161] op_sel:[0,1]
	v_pk_mul_f32 v[66:67], v[66:67], v[160:161] op_sel:[0,1]
	v_pk_mul_f32 v[68:69], v[68:69], v[160:161] op_sel:[0,1]
	v_add_u32_e32 v160, 0x90, v150
	v_ashrrev_i32_e32 v161, 31, v160
	v_lshlrev_b64 v[192:193], 12, v[160:161]
	v_lshl_add_u64 v[192:193], s[0:1], 0, v[192:193]
	v_lshl_add_u64 v[192:193], v[192:193], 0, v[168:169]
	s_waitcnt vmcnt(6)
	v_pk_fma_f32 v[80:81], v[136:137], v[80:81], v[246:247]
	v_pk_fma_f32 v[78:79], v[134:135], v[78:79], v[244:245]
	s_waitcnt vmcnt(5)
	v_pk_fma_f32 v[76:77], v[132:133], v[76:77], v[254:255]
	v_pk_fma_f32 v[74:75], v[130:131], v[74:75], v[252:253]
	s_waitcnt vmcnt(4)
	v_pk_fma_f32 v[72:73], v[144:145], v[72:73], v[218:219]
	v_pk_fma_f32 v[70:71], v[142:143], v[70:71], v[216:217]
	s_waitcnt vmcnt(3)
	v_pk_fma_f32 v[68:69], v[140:141], v[68:69], v[222:223]
	v_pk_fma_f32 v[66:67], v[138:139], v[66:67], v[220:221]
	s_nop 0
	v_add_u32_e32 v250, 0x80000, v231
	global_load_dwordx4 v[244:247], v250, s[100:101] offset:576
	v_add_u32_e32 v250, 0x90000, v231
	global_load_dwordx4 v[252:255], v250, s[100:101]
	global_load_dwordx4 v[216:219], v250, s[100:101] offset:64
	global_load_dwordx4 v[220:223], v250, s[100:101] offset:512
	ds_read_b64 v[180:181], v184 offset:9216
	s_waitcnt lgkmcnt(0)
	v_pk_mul_f32 v[62:63], v[62:63], v[180:181] op_sel:[0,1]
	v_pk_mul_f32 v[64:65], v[64:65], v[180:181] op_sel:[0,1]
	v_pk_mul_f32 v[58:59], v[58:59], v[180:181] op_sel:[0,1]
	v_pk_mul_f32 v[60:61], v[60:61], v[180:181] op_sel:[0,1]
	v_pk_mul_f32 v[54:55], v[54:55], v[180:181] op_sel:[0,1]
	v_pk_mul_f32 v[56:57], v[56:57], v[180:181] op_sel:[0,1]
	v_pk_mul_f32 v[50:51], v[50:51], v[180:181] op_sel:[0,1]
	v_pk_mul_f32 v[52:53], v[52:53], v[180:181] op_sel:[0,1]
	s_waitcnt vmcnt(6)
	v_pk_fma_f32 v[64:65], v[136:137], v[64:65], v[234:235]
	v_pk_fma_f32 v[62:63], v[134:135], v[62:63], v[232:233]
	s_waitcnt vmcnt(5)
	v_pk_fma_f32 v[60:61], v[132:133], v[60:61], v[238:239]
	v_pk_fma_f32 v[58:59], v[130:131], v[58:59], v[236:237]
	s_waitcnt vmcnt(4)
	v_pk_fma_f32 v[56:57], v[144:145], v[56:57], v[242:243]
	v_pk_fma_f32 v[54:55], v[142:143], v[54:55], v[240:241]
	s_waitcnt vmcnt(3)
	v_pk_fma_f32 v[52:53], v[140:141], v[52:53], v[246:247]
	v_pk_fma_f32 v[50:51], v[138:139], v[50:51], v[244:245]
	v_add_u32_e32 v164, 0xa0, v150
	v_add_u32_e32 v250, 0x90000, v231
	global_load_dwordx4 v[232:235], v250, s[100:101] offset:576
	v_add_u32_e32 v250, 0xa0000, v231
	global_load_dwordx4 v[236:239], v250, s[100:101]
	global_load_dwordx4 v[240:243], v250, s[100:101] offset:64
	global_load_dwordx4 v[244:247], v250, s[100:101] offset:512
	s_nop 0
	ds_read_b64 v[166:167], v184 offset:9344
	v_ashrrev_i32_e32 v165, 31, v164
	v_lshlrev_b64 v[180:181], 12, v[164:165]
	v_lshl_add_u64 v[180:181], s[0:1], 0, v[180:181]
	v_lshl_add_u64 v[180:181], v[180:181], 0, v[168:169]
	s_waitcnt lgkmcnt(0)
	v_pk_mul_f32 v[46:47], v[46:47], v[166:167] op_sel:[0,1]
	v_pk_mul_f32 v[48:49], v[48:49], v[166:167] op_sel:[0,1]
	v_pk_mul_f32 v[42:43], v[42:43], v[166:167] op_sel:[0,1]
	v_pk_mul_f32 v[44:45], v[44:45], v[166:167] op_sel:[0,1]
	v_pk_mul_f32 v[38:39], v[38:39], v[166:167] op_sel:[0,1]
	v_pk_mul_f32 v[40:41], v[40:41], v[166:167] op_sel:[0,1]
	v_pk_mul_f32 v[34:35], v[34:35], v[166:167] op_sel:[0,1]
	v_pk_mul_f32 v[36:37], v[36:37], v[166:167] op_sel:[0,1]
	v_add_u32_e32 v166, 0xb0, v150
	v_ashrrev_i32_e32 v167, 31, v166
	s_waitcnt vmcnt(6)
	v_pk_fma_f32 v[48:49], v[136:137], v[48:49], v[254:255]
	v_pk_fma_f32 v[46:47], v[134:135], v[46:47], v[252:253]
	s_waitcnt vmcnt(5)
	v_pk_fma_f32 v[44:45], v[132:133], v[44:45], v[218:219]
	v_pk_fma_f32 v[42:43], v[130:131], v[42:43], v[216:217]
	s_waitcnt vmcnt(4)
	v_pk_fma_f32 v[40:41], v[144:145], v[40:41], v[222:223]
	v_pk_fma_f32 v[38:39], v[142:143], v[38:39], v[220:221]
	s_waitcnt vmcnt(3)
	v_pk_fma_f32 v[36:37], v[140:141], v[36:37], v[234:235]
	v_pk_fma_f32 v[34:35], v[138:139], v[34:35], v[232:233]
	s_nop 0
	v_add_u32_e32 v250, 0xa0000, v231
	global_load_dwordx4 v[252:255], v250, s[100:101] offset:576
	v_add_u32_e32 v250, 0xb0000, v231
	global_load_dwordx4 v[216:219], v250, s[100:101]
	global_load_dwordx4 v[220:223], v250, s[100:101] offset:64
	global_load_dwordx4 v[232:235], v250, s[100:101] offset:512
	ds_read_b64 v[210:211], v184 offset:9472
	v_lshlrev_b64 v[180:181], 12, v[166:167]
	v_lshl_add_u64 v[180:181], s[0:1], 0, v[180:181]
	v_lshl_add_u64 v[168:169], v[180:181], 0, v[168:169]
	v_mov_b32_e32 v180, v119
	s_waitcnt lgkmcnt(0)
	v_pk_mul_f32 v[30:31], v[30:31], v[210:211] op_sel:[0,1]
	v_pk_mul_f32 v[32:33], v[32:33], v[210:211] op_sel:[0,1]
	v_pk_mul_f32 v[26:27], v[26:27], v[210:211] op_sel:[0,1]
	v_pk_mul_f32 v[28:29], v[28:29], v[210:211] op_sel:[0,1]
	v_pk_mul_f32 v[22:23], v[22:23], v[210:211] op_sel:[0,1]
	v_pk_mul_f32 v[24:25], v[24:25], v[210:211] op_sel:[0,1]
	v_pk_mul_f32 v[18:19], v[18:19], v[210:211] op_sel:[0,1]
	v_pk_mul_f32 v[20:21], v[20:21], v[210:211] op_sel:[0,1]
	v_mov_b32_e32 v181, v120
	s_waitcnt vmcnt(6)
	v_pk_fma_f32 v[32:33], v[136:137], v[32:33], v[238:239]
	v_pk_fma_f32 v[30:31], v[134:135], v[30:31], v[236:237]
	s_waitcnt vmcnt(5)
	v_pk_fma_f32 v[28:29], v[132:133], v[28:29], v[242:243]
	v_pk_fma_f32 v[26:27], v[130:131], v[26:27], v[240:241]
	s_waitcnt vmcnt(4)
	v_pk_fma_f32 v[24:25], v[144:145], v[24:25], v[246:247]
	v_pk_fma_f32 v[22:23], v[142:143], v[22:23], v[244:245]
	s_waitcnt vmcnt(3)
	v_pk_fma_f32 v[20:21], v[140:141], v[20:21], v[254:255]
	v_pk_fma_f32 v[18:19], v[138:139], v[18:19], v[252:253]
	v_pk_add_f32 v[172:173], v[180:181], v[196:197]
	v_add_u32_e32 v250, 0xb0000, v231
	global_load_dwordx4 v[236:239], v250, s[100:101] offset:576
	v_pk_add_f32 v[196:197], v[204:205], v[206:207]
	v_add_f32_e32 v172, v172, v173
	v_pk_add_f32 v[168:169], v[196:197], v[196:197] op_sel_hi:[0,1]
	v_add_f32_e32 v215, 0, v172
	v_mov_b32_e32 v168, v116
	v_pk_add_f32 v[204:205], v[208:209], v[212:213]
	v_pk_add_f32 v[168:169], v[168:169], v[214:215]
	s_nop 0
	v_pk_add_f32 v[168:169], v[204:205], v[168:169]
	s_nop 0
	v_add_f32_e32 v168, v168, v169
	v_mov_b32_e32 v169, v168
	s_nop 1
	v_permlane16_swap_b32_e32 v168, v169
	s_waitcnt lgkmcnt(0)
	v_add_f32_e32 v168, v168, v169
	v_mov_b32_e32 v169, v168
	s_nop 1
	v_permlane32_swap_b32_e32 v168, v169
	s_waitcnt lgkmcnt(0)
	v_add_f32_e32 v168, v168, v169
	v_fmamk_f32 v172, v168, 0xbc800000, v121
	v_fmamk_f32 v187, v168, 0xbc800000, v119
	v_fmamk_f32 v197, v168, 0xbc800000, v125
	v_fmamk_f32 v205, v168, 0xbc800000, v123
	v_fmamk_f32 v169, v168, 0xbc800000, v120
	v_fmamk_f32 v173, v168, 0xbc800000, v118
	v_fmamk_f32 v196, v168, 0xbc800000, v124
	v_fmamk_f32 v204, v168, 0xbc800000, v122
	v_fmamk_f32 v207, v168, 0xbc800000, v129
	v_fmamk_f32 v209, v168, 0xbc800000, v127
	v_mul_f32_e32 v187, v187, v187
	v_mul_f32_e32 v172, v172, v172
	v_mul_f32_e32 v205, v205, v205
	v_mul_f32_e32 v197, v197, v197
	v_fmamk_f32 v206, v168, 0xbc800000, v128
	v_fmamk_f32 v208, v168, 0xbc800000, v126
	v_fmamk_f32 v211, v168, 0xbc800000, v117
	v_fmamk_f32 v213, v168, 0xbc800000, v115
	v_mul_f32_e32 v209, v209, v209
	v_mul_f32_e32 v207, v207, v207
	v_fmac_f32_e32 v187, v173, v173
	v_fmac_f32_e32 v172, v169, v169
	v_fmac_f32_e32 v205, v204, v204
	v_fmac_f32_e32 v197, v196, v196
	v_fmamk_f32 v210, v168, 0xbc800000, v116
	v_fmamk_f32 v212, v168, 0xbc800000, v114
	v_mul_f32_e32 v213, v213, v213
	v_mul_f32_e32 v211, v211, v211
	v_fmac_f32_e32 v209, v208, v208
	v_fmac_f32_e32 v207, v206, v206
	v_add_f32_e32 v169, v187, v172
	v_add_f32_e32 v172, v205, v197
	v_fmac_f32_e32 v213, v212, v212
	v_fmac_f32_e32 v211, v210, v210
	v_add_f32_e32 v173, v209, v207
	v_add_f32_e32 v169, v169, v172
	v_add_f32_e32 v187, v213, v211
	v_add_f32_e32 v169, v173, v169
	v_add_f32_e32 v169, v187, v169
	v_mov_b32_e32 v172, v169
	s_nop 1
	v_permlane16_swap_b32_e32 v169, v172
	ds_read_b64 v[196:197], v184 offset:9600
	s_waitcnt lgkmcnt(1)
	v_add_f32_e32 v169, v169, v172
	ds_bpermute_b32 v172, v202, v169
	s_waitcnt lgkmcnt(1)
	v_pk_mul_f32 v[14:15], v[14:15], v[196:197] op_sel:[0,1]
	v_pk_mul_f32 v[16:17], v[16:17], v[196:197] op_sel:[0,1]
	v_pk_mul_f32 v[10:11], v[10:11], v[196:197] op_sel:[0,1]
	v_pk_mul_f32 v[12:13], v[12:13], v[196:197] op_sel:[0,1]
	v_pk_mul_f32 v[6:7], v[6:7], v[196:197] op_sel:[0,1]
	v_pk_mul_f32 v[8:9], v[8:9], v[196:197] op_sel:[0,1]
	v_pk_mul_f32 v[2:3], v[2:3], v[196:197] op_sel:[0,1]
	v_pk_mul_f32 v[4:5], v[4:5], v[196:197] op_sel:[0,1]
	s_waitcnt vmcnt(3)
	v_pk_fma_f32 v[16:17], v[136:137], v[16:17], v[218:219]
	v_pk_fma_f32 v[14:15], v[134:135], v[14:15], v[216:217]
	s_waitcnt vmcnt(2)
	v_pk_fma_f32 v[12:13], v[132:133], v[12:13], v[222:223]
	v_pk_fma_f32 v[10:11], v[130:131], v[10:11], v[220:221]
	s_waitcnt vmcnt(1)
	v_pk_fma_f32 v[8:9], v[144:145], v[8:9], v[234:235]
	v_pk_fma_f32 v[6:7], v[142:143], v[6:7], v[232:233]
	s_waitcnt vmcnt(0)
	v_pk_fma_f32 v[4:5], v[140:141], v[4:5], v[238:239]
	v_pk_fma_f32 v[2:3], v[138:139], v[2:3], v[236:237]
	s_nop 0
	s_and_saveexec_b64 s[0:1], s[4:5]
	s_cbranch_execz .LBB0_612
	s_lshl_b32 s17, s26, 11
	s_add_i32 s17, s27, s17
	v_mul_f32_e32 v130, 0x3c800000, v168
	s_waitcnt lgkmcnt(0)
	v_add_f32_e32 v131, v169, v172
	v_lshl_add_u32 v132, v170, 5, s17
	ds_write_b64 v132, v[130:131]
